# v9 plus remaining eight in-proj LDS-DMA loads in saddr form (second-k-step bases via two SALU adds): no VALU left in the GEMM load segments
# baseline (speedup 1.0000x reference)
.LBB0_259:
	s_add_u32 s13, s40, 0xfff80080
	s_addc_u32 s36, s41, -1
	s_add_i32 s37, 0, 0x10000
	ds_read_b128 v[142:145], v146
	ds_read_b128 v[152:155], v146 offset:1024
	ds_read_b128 v[156:159], v146 offset:2048
	ds_read_b128 v[160:163], v146 offset:3072
	s_cmp_eq_u32 s81, 28
	s_cselect_b32 s45, s19, s36
	s_cselect_b32 s44, s24, s13
	s_cselect_b32 s43, s17, s80
	s_cselect_b32 s42, s25, s33
	s_add_i32 m0, s69, 0xc000
	ds_read_b128 v[164:167], v150
	ds_read_b128 v[168:171], v150 offset:1024
	ds_read_b128 v[172:175], v150 offset:2048
	ds_read_b128 v[176:179], v150 offset:3072
	ds_read_b128 v[180:183], v150 offset:4096
	ds_read_b128 v[184:187], v150 offset:5120
	ds_read_b128 v[188:191], v150 offset:6144
	ds_read_b128 v[192:195], v150 offset:7168
	global_load_lds_dwordx4 v138, s[40:41]
	s_add_i32 m0, s69, 0xe000
	s_nop 0
	global_load_lds_dwordx4 v140, s[40:41]
	s_waitcnt lgkmcnt(8)
	s_barrier
	s_waitcnt lgkmcnt(0)
	v_mfma_f32_16x16x32_bf16 v[126:129], v[142:145], v[164:167], v[126:129]
	v_mfma_f32_16x16x32_bf16 v[122:125], v[156:159], v[164:167], v[122:125]
	v_mfma_f32_16x16x32_bf16 v[110:113], v[142:145], v[172:175], v[110:113]
	v_mfma_f32_16x16x32_bf16 v[106:109], v[156:159], v[172:175], v[106:109]
	v_mfma_f32_16x16x32_bf16 v[94:97], v[142:145], v[180:183], v[94:97]
	v_mfma_f32_16x16x32_bf16 v[90:93], v[156:159], v[180:183], v[90:93]
	v_mfma_f32_16x16x32_bf16 v[78:81], v[142:145], v[188:191], v[78:81]
	v_mfma_f32_16x16x32_bf16 v[74:77], v[156:159], v[188:191], v[74:77]
	v_mfma_f32_16x16x32_bf16 v[126:129], v[152:155], v[168:171], v[126:129]
	v_mfma_f32_16x16x32_bf16 v[122:125], v[160:163], v[168:171], v[122:125]
	v_mfma_f32_16x16x32_bf16 v[110:113], v[152:155], v[176:179], v[110:113]
	v_mfma_f32_16x16x32_bf16 v[106:109], v[160:163], v[176:179], v[106:109]
	v_mfma_f32_16x16x32_bf16 v[94:97], v[152:155], v[184:187], v[94:97]
	v_mfma_f32_16x16x32_bf16 v[90:93], v[160:163], v[184:187], v[90:93]
	v_mfma_f32_16x16x32_bf16 v[78:81], v[152:155], v[192:195], v[78:81]
	v_mfma_f32_16x16x32_bf16 v[74:77], v[160:163], v[192:195], v[74:77]
	s_barrier
	s_add_i32 s13, 0, 0x14000
	s_add_i32 s36, s37, s48
	s_mov_b32 m0, s36
	ds_read_b128 v[196:199], v146 offset:16384
	ds_read_b128 v[200:203], v146 offset:17408
	ds_read_b128 v[216:219], v146 offset:18432
	ds_read_b128 v[232:235], v146 offset:19456
	global_load_lds_dwordx4 v134, s[42:43]
	s_add_i32 m0, s36, 0x2000
	s_nop 0
	global_load_lds_dwordx4 v130, s[42:43]
	s_barrier
	s_waitcnt lgkmcnt(0)
	v_mfma_f32_16x16x32_bf16 v[118:121], v[196:199], v[164:167], v[118:121]
	v_mfma_f32_16x16x32_bf16 v[114:117], v[216:219], v[164:167], v[114:117]
	v_mfma_f32_16x16x32_bf16 v[102:105], v[196:199], v[172:175], v[102:105]
	v_mfma_f32_16x16x32_bf16 v[98:101], v[216:219], v[172:175], v[98:101]
	v_mfma_f32_16x16x32_bf16 v[86:89], v[196:199], v[180:183], v[86:89]
	v_mfma_f32_16x16x32_bf16 v[82:85], v[216:219], v[180:183], v[82:85]
	v_mfma_f32_16x16x32_bf16 v[70:73], v[196:199], v[188:191], v[70:73]
	v_mfma_f32_16x16x32_bf16 v[66:69], v[216:219], v[188:191], v[66:69]
	v_mfma_f32_16x16x32_bf16 v[118:121], v[200:203], v[168:171], v[118:121]
	v_mfma_f32_16x16x32_bf16 v[114:117], v[232:235], v[168:171], v[114:117]
	v_mfma_f32_16x16x32_bf16 v[102:105], v[200:203], v[176:179], v[102:105]
	v_mfma_f32_16x16x32_bf16 v[98:101], v[232:235], v[176:179], v[98:101]
	v_mfma_f32_16x16x32_bf16 v[86:89], v[200:203], v[184:187], v[86:89]
	v_mfma_f32_16x16x32_bf16 v[82:85], v[232:235], v[184:187], v[82:85]
	v_mfma_f32_16x16x32_bf16 v[70:73], v[200:203], v[192:195], v[70:73]
	v_mfma_f32_16x16x32_bf16 v[66:69], v[232:235], v[192:195], v[66:69]
	s_mov_b32 m0, s69
	s_barrier
	ds_read_b128 v[164:167], v150 offset:16384
	ds_read_b128 v[168:171], v150 offset:17408
	ds_read_b128 v[172:175], v150 offset:18432
	ds_read_b128 v[176:179], v150 offset:19456
	ds_read_b128 v[180:183], v150 offset:20480
	ds_read_b128 v[184:187], v150 offset:21504
	ds_read_b128 v[188:191], v150 offset:22528
	ds_read_b128 v[192:195], v150 offset:23552
	global_load_lds_dwordx4 v136, s[44:45]
	s_mov_b32 m0, s86
	s_nop 0
	global_load_lds_dwordx4 v132, s[44:45]
	s_barrier
	s_waitcnt lgkmcnt(0)
	v_mfma_f32_16x16x32_bf16 v[62:65], v[142:145], v[164:167], v[62:65]
	v_mfma_f32_16x16x32_bf16 v[58:61], v[156:159], v[164:167], v[58:61]
	v_mfma_f32_16x16x32_bf16 v[46:49], v[142:145], v[172:175], v[46:49]
	v_mfma_f32_16x16x32_bf16 v[42:45], v[156:159], v[172:175], v[42:45]
	v_mfma_f32_16x16x32_bf16 v[30:33], v[142:145], v[180:183], v[30:33]
	v_mfma_f32_16x16x32_bf16 v[26:29], v[156:159], v[180:183], v[26:29]
	v_mfma_f32_16x16x32_bf16 v[14:17], v[142:145], v[188:191], v[14:17]
	v_mfma_f32_16x16x32_bf16 v[10:13], v[156:159], v[188:191], v[10:13]
	v_mfma_f32_16x16x32_bf16 v[62:65], v[152:155], v[168:171], v[62:65]
	v_mfma_f32_16x16x32_bf16 v[58:61], v[160:163], v[168:171], v[58:61]
	v_mfma_f32_16x16x32_bf16 v[46:49], v[152:155], v[176:179], v[46:49]
	v_mfma_f32_16x16x32_bf16 v[42:45], v[160:163], v[176:179], v[42:45]
	v_mfma_f32_16x16x32_bf16 v[30:33], v[152:155], v[184:187], v[30:33]
	v_mfma_f32_16x16x32_bf16 v[26:29], v[160:163], v[184:187], v[26:29]
	v_mfma_f32_16x16x32_bf16 v[14:17], v[152:155], v[192:195], v[14:17]
	v_mfma_f32_16x16x32_bf16 v[10:13], v[160:163], v[192:195], v[10:13]
	s_barrier
	s_add_u32 s96, s42, 0x80000
	s_addc_u32 s97, s43, 0
	s_add_i32 s13, s13, s48
	s_mov_b32 m0, s13
	s_nop 0
	global_load_lds_dwordx4 v134, s[96:97]
	s_add_i32 m0, s13, 0x2000
	s_nop 0
	global_load_lds_dwordx4 v130, s[96:97]
	s_waitcnt vmcnt(6)
	s_barrier
	v_mfma_f32_16x16x32_bf16 v[54:57], v[196:199], v[164:167], v[54:57]
	v_mfma_f32_16x16x32_bf16 v[50:53], v[216:219], v[164:167], v[50:53]
	v_mfma_f32_16x16x32_bf16 v[38:41], v[196:199], v[172:175], v[38:41]
	v_mfma_f32_16x16x32_bf16 v[34:37], v[216:219], v[172:175], v[34:37]
	v_mfma_f32_16x16x32_bf16 v[22:25], v[196:199], v[180:183], v[22:25]
	v_mfma_f32_16x16x32_bf16 v[18:21], v[216:219], v[180:183], v[18:21]
	v_mfma_f32_16x16x32_bf16 v[6:9], v[196:199], v[188:191], v[6:9]
	v_mfma_f32_16x16x32_bf16 v[2:5], v[216:219], v[188:191], v[2:5]
	v_mfma_f32_16x16x32_bf16 v[54:57], v[200:203], v[168:171], v[54:57]
	v_mfma_f32_16x16x32_bf16 v[50:53], v[232:235], v[168:171], v[50:53]
	v_mfma_f32_16x16x32_bf16 v[38:41], v[200:203], v[176:179], v[38:41]
	v_mfma_f32_16x16x32_bf16 v[34:37], v[232:235], v[176:179], v[34:37]
	v_mfma_f32_16x16x32_bf16 v[22:25], v[200:203], v[184:187], v[22:25]
	v_mfma_f32_16x16x32_bf16 v[18:21], v[232:235], v[184:187], v[18:21]
	v_mfma_f32_16x16x32_bf16 v[6:9], v[200:203], v[192:195], v[6:9]
	v_mfma_f32_16x16x32_bf16 v[2:5], v[232:235], v[192:195], v[2:5]
	s_add_i32 s13, 0, 0x18000
	s_barrier
	ds_read_b128 v[142:145], v146 offset:32768
	ds_read_b128 v[152:155], v146 offset:33792
	ds_read_b128 v[156:159], v146 offset:34816
	ds_read_b128 v[160:163], v146 offset:35840
	s_add_u32 s44, s44, 0x80000
	s_addc_u32 s45, s45, 0
	s_mov_b32 m0, s87
	ds_read_b128 v[164:167], v150 offset:32768
	ds_read_b128 v[168:171], v150 offset:33792
	ds_read_b128 v[172:175], v150 offset:34816
	ds_read_b128 v[176:179], v150 offset:35840
	ds_read_b128 v[180:183], v150 offset:36864
	ds_read_b128 v[184:187], v150 offset:37888
	ds_read_b128 v[188:191], v150 offset:38912
	ds_read_b128 v[192:195], v150 offset:39936
	global_load_lds_dwordx4 v136, s[44:45]
	s_mov_b32 m0, s90
	s_nop 0
	global_load_lds_dwordx4 v132, s[44:45]
	s_waitcnt lgkmcnt(8)
	s_barrier
	s_waitcnt lgkmcnt(0)
	v_mfma_f32_16x16x32_bf16 v[126:129], v[142:145], v[164:167], v[126:129]
	v_mfma_f32_16x16x32_bf16 v[122:125], v[156:159], v[164:167], v[122:125]
	v_mfma_f32_16x16x32_bf16 v[110:113], v[142:145], v[172:175], v[110:113]
	v_mfma_f32_16x16x32_bf16 v[106:109], v[156:159], v[172:175], v[106:109]
	v_mfma_f32_16x16x32_bf16 v[94:97], v[142:145], v[180:183], v[94:97]
	v_mfma_f32_16x16x32_bf16 v[90:93], v[156:159], v[180:183], v[90:93]
	v_mfma_f32_16x16x32_bf16 v[78:81], v[142:145], v[188:191], v[78:81]
	v_mfma_f32_16x16x32_bf16 v[74:77], v[156:159], v[188:191], v[74:77]
	v_mfma_f32_16x16x32_bf16 v[126:129], v[152:155], v[168:171], v[126:129]
	v_mfma_f32_16x16x32_bf16 v[122:125], v[160:163], v[168:171], v[122:125]
	v_mfma_f32_16x16x32_bf16 v[110:113], v[152:155], v[176:179], v[110:113]
	v_mfma_f32_16x16x32_bf16 v[106:109], v[160:163], v[176:179], v[106:109]
	v_mfma_f32_16x16x32_bf16 v[94:97], v[152:155], v[184:187], v[94:97]
	v_mfma_f32_16x16x32_bf16 v[90:93], v[160:163], v[184:187], v[90:93]
	v_mfma_f32_16x16x32_bf16 v[78:81], v[152:155], v[192:195], v[78:81]
	v_mfma_f32_16x16x32_bf16 v[74:77], v[160:163], v[192:195], v[74:77]
	s_barrier
	s_add_i32 s36, 0, 0x1c000
	s_add_i32 s13, s13, s48
	s_add_u32 s100, s42, 0x80
	s_addc_u32 s101, s43, 0
	s_mov_b32 m0, s13
	ds_read_b128 v[196:199], v146 offset:49152
	ds_read_b128 v[200:203], v146 offset:50176
	ds_read_b128 v[216:219], v146 offset:51200
	ds_read_b128 v[232:235], v146 offset:52224
	global_load_lds_dwordx4 v134, s[100:101]
	s_add_i32 m0, s13, 0x2000
	s_nop 0
	global_load_lds_dwordx4 v130, s[100:101]
	s_barrier
	s_waitcnt lgkmcnt(0)
	v_mfma_f32_16x16x32_bf16 v[118:121], v[196:199], v[164:167], v[118:121]
	v_mfma_f32_16x16x32_bf16 v[114:117], v[216:219], v[164:167], v[114:117]
	v_mfma_f32_16x16x32_bf16 v[102:105], v[196:199], v[172:175], v[102:105]
	v_mfma_f32_16x16x32_bf16 v[98:101], v[216:219], v[172:175], v[98:101]
	v_mfma_f32_16x16x32_bf16 v[86:89], v[196:199], v[180:183], v[86:89]
	v_mfma_f32_16x16x32_bf16 v[82:85], v[216:219], v[180:183], v[82:85]
	v_mfma_f32_16x16x32_bf16 v[70:73], v[196:199], v[188:191], v[70:73]
	v_mfma_f32_16x16x32_bf16 v[66:69], v[216:219], v[188:191], v[66:69]
	v_mfma_f32_16x16x32_bf16 v[118:121], v[200:203], v[168:171], v[118:121]
	v_mfma_f32_16x16x32_bf16 v[114:117], v[232:235], v[168:171], v[114:117]
	v_mfma_f32_16x16x32_bf16 v[102:105], v[200:203], v[176:179], v[102:105]
	v_mfma_f32_16x16x32_bf16 v[98:101], v[232:235], v[176:179], v[98:101]
	v_mfma_f32_16x16x32_bf16 v[86:89], v[200:203], v[184:187], v[86:89]
	v_mfma_f32_16x16x32_bf16 v[82:85], v[232:235], v[184:187], v[82:85]
	v_mfma_f32_16x16x32_bf16 v[70:73], v[200:203], v[192:195], v[70:73]
	v_mfma_f32_16x16x32_bf16 v[66:69], v[232:235], v[192:195], v[66:69]
	s_mov_b32 m0, s91
	s_add_u32 s100, s44, 0xfff80080
	s_addc_u32 s101, s45, -1
	s_barrier
	ds_read_b128 v[164:167], v150 offset:49152
	ds_read_b128 v[168:171], v150 offset:50176
	ds_read_b128 v[172:175], v150 offset:51200
	ds_read_b128 v[176:179], v150 offset:52224
	ds_read_b128 v[180:183], v150 offset:53248
	ds_read_b128 v[184:187], v150 offset:54272
	ds_read_b128 v[188:191], v150 offset:55296
	ds_read_b128 v[192:195], v150 offset:56320
	global_load_lds_dwordx4 v136, s[100:101]
	s_mov_b32 m0, s26
	s_nop 0
	global_load_lds_dwordx4 v132, s[100:101]
	s_barrier
	s_waitcnt lgkmcnt(0)
	v_mfma_f32_16x16x32_bf16 v[62:65], v[142:145], v[164:167], v[62:65]
	v_mfma_f32_16x16x32_bf16 v[58:61], v[156:159], v[164:167], v[58:61]
	v_mfma_f32_16x16x32_bf16 v[46:49], v[142:145], v[172:175], v[46:49]
	v_mfma_f32_16x16x32_bf16 v[42:45], v[156:159], v[172:175], v[42:45]
	v_mfma_f32_16x16x32_bf16 v[30:33], v[142:145], v[180:183], v[30:33]
	v_mfma_f32_16x16x32_bf16 v[26:29], v[156:159], v[180:183], v[26:29]
	v_mfma_f32_16x16x32_bf16 v[14:17], v[142:145], v[188:191], v[14:17]
	v_mfma_f32_16x16x32_bf16 v[10:13], v[156:159], v[188:191], v[10:13]
	v_mfma_f32_16x16x32_bf16 v[62:65], v[152:155], v[168:171], v[62:65]
	v_mfma_f32_16x16x32_bf16 v[58:61], v[160:163], v[168:171], v[58:61]
	v_mfma_f32_16x16x32_bf16 v[46:49], v[152:155], v[176:179], v[46:49]
	v_mfma_f32_16x16x32_bf16 v[42:45], v[160:163], v[176:179], v[42:45]
	v_mfma_f32_16x16x32_bf16 v[30:33], v[152:155], v[184:187], v[30:33]
	v_mfma_f32_16x16x32_bf16 v[26:29], v[160:163], v[184:187], v[26:29]
	v_mfma_f32_16x16x32_bf16 v[14:17], v[152:155], v[192:195], v[14:17]
	v_mfma_f32_16x16x32_bf16 v[10:13], v[160:163], v[192:195], v[10:13]
	s_barrier
	s_add_u32 s42, s42, 0x80080
	s_addc_u32 s43, s43, 0
	s_add_i32 s13, s36, s48
	s_mov_b32 m0, s13
	s_nop 0
	global_load_lds_dwordx4 v134, s[42:43]
	s_add_i32 m0, s13, 0x2000
	s_nop 0
	global_load_lds_dwordx4 v130, s[42:43]
	s_waitcnt vmcnt(6)
	s_barrier
	v_mfma_f32_16x16x32_bf16 v[54:57], v[196:199], v[164:167], v[54:57]
	v_mfma_f32_16x16x32_bf16 v[50:53], v[216:219], v[164:167], v[50:53]
	v_mfma_f32_16x16x32_bf16 v[38:41], v[196:199], v[172:175], v[38:41]
	v_mfma_f32_16x16x32_bf16 v[34:37], v[216:219], v[172:175], v[34:37]
	v_mfma_f32_16x16x32_bf16 v[22:25], v[196:199], v[180:183], v[22:25]
	v_mfma_f32_16x16x32_bf16 v[18:21], v[216:219], v[180:183], v[18:21]
	v_mfma_f32_16x16x32_bf16 v[6:9], v[196:199], v[188:191], v[6:9]
	v_mfma_f32_16x16x32_bf16 v[2:5], v[216:219], v[188:191], v[2:5]
	v_mfma_f32_16x16x32_bf16 v[54:57], v[200:203], v[168:171], v[54:57]
	v_mfma_f32_16x16x32_bf16 v[50:53], v[232:235], v[168:171], v[50:53]
	v_mfma_f32_16x16x32_bf16 v[38:41], v[200:203], v[176:179], v[38:41]
	v_mfma_f32_16x16x32_bf16 v[34:37], v[232:235], v[176:179], v[34:37]
	v_mfma_f32_16x16x32_bf16 v[22:25], v[200:203], v[184:187], v[22:25]
	v_mfma_f32_16x16x32_bf16 v[18:21], v[232:235], v[184:187], v[18:21]
	v_mfma_f32_16x16x32_bf16 v[6:9], v[200:203], v[192:195], v[6:9]
	v_mfma_f32_16x16x32_bf16 v[2:5], v[232:235], v[192:195], v[2:5]
	s_add_i32 s81, s81, 2
	s_add_u32 s40, s40, 0x100
	s_addc_u32 s41, s41, 0
	s_add_u32 s33, s33, 0x100
	s_addc_u32 s80, s80, 0
	s_cmp_gt_u32 s81, 29
	s_barrier
	s_cbranch_scc0 .LBB0_259
	s_cmp_lg_u32 s12, s46
	v_lshl_add_u32 v144, s12, 8, v1
	s_cselect_b64 s[42:43], -1, 0
	s_mov_b64 s[24:25], -1
	s_and_b64 vcc, exec, s[42:43]
	v_ashrrev_i32_e32 v145, 31, v144
	s_cbranch_vccz .LBB0_262
	v_lshl_add_u64 v[142:143], v[144:145], 2, s[0:1]
	v_add_co_u32_e32 v152, vcc, 0x8000, v142
	global_load_dword v146, v[142:143], off
	s_nop 0
	v_addc_co_u32_e32 v153, vcc, 0, v143, vcc
	global_load_dword v151, v[152:153], off
	v_add_co_u32_e32 v152, vcc, 0x10000, v142
	s_mov_b64 s[24:25], 0
	s_nop 0
	v_addc_co_u32_e32 v153, vcc, 0, v143, vcc
	s_waitcnt vmcnt(0)
	v_add_f32_e32 v146, 0, v146
	v_add_f32_e32 v146, v146, v151
	global_load_dword v151, v[152:153], off
	v_add_co_u32_e32 v152, vcc, 0x18000, v142
	s_waitcnt vmcnt(0)
	v_add_f32_e32 v146, v146, v151
	v_addc_co_u32_e32 v153, vcc, 0, v143, vcc
	global_load_dword v151, v[152:153], off
	v_add_co_u32_e32 v152, vcc, s5, v142
	s_waitcnt vmcnt(0)
	v_add_f32_e32 v146, v146, v151
	v_addc_co_u32_e32 v153, vcc, 0, v143, vcc
	global_load_dword v151, v[152:153], off
	v_add_co_u32_e32 v152, vcc, 0x28000, v142
	s_waitcnt vmcnt(0)
	v_add_f32_e32 v146, v146, v151
	v_addc_co_u32_e32 v153, vcc, 0, v143, vcc
	global_load_dword v151, v[152:153], off
	v_add_co_u32_e32 v152, vcc, 0x30000, v142
	s_waitcnt vmcnt(0)
	v_add_f32_e32 v146, v146, v151
	v_addc_co_u32_e32 v153, vcc, 0, v143, vcc
	v_add_co_u32_e32 v142, vcc, 0x38000, v142
	global_load_dword v151, v[152:153], off
	s_nop 0
	v_addc_co_u32_e32 v143, vcc, 0, v143, vcc
	global_load_dword v142, v[142:143], off
	s_waitcnt vmcnt(0)
	v_add_f32_e32 v146, v146, v151
	v_add_f32_e32 v142, v146, v142
	v_fmamk_f32 v142, v142, 0x3a000000, v223
	v_cmp_gt_f32_e32 vcc, s4, v142
	v_mul_f32_e32 v143, 0x4b800000, v142
	s_nop 0
	v_cndmask_b32_e32 v142, v142, v143, vcc
	v_rsq_f32_e32 v142, v142
	s_nop 0
	v_mul_f32_e32 v143, 0x45800000, v142
	v_cndmask_b32_e32 v146, v142, v143, vcc
